# rwkv scan inner loops hand-scheduled: 16 steps unrolled, y/loads fill DPP wait states, chain shortened
# speedup vs baseline: 1.0261x; 1.0227x over previous
.LBB0_203:
	s_or_b64 exec, exec, s[6:7]
	s_and_b64 s[0:1], exec, vcc
	s_or_b64 s[60:61], s[0:1], s[60:61]
	ds_read_b128 v[16:19], v94 offset:12288
	ds_read_b128 v[12:15], v94 offset:8192
	ds_read_b32 v74, v39 offset:20480
	ds_read_b128 v[24:27], v94 offset:4096
	ds_read_b128 v[20:23], v94 offset:16384
	ds_read_b128 v[28:31], v94 offset:0
	s_waitcnt lgkmcnt(3)
	v_pk_mul_f32 v[16:17], v[8:9], v[16:17]
	v_pk_mul_f32 v[12:13], v[12:13], v[74:75] op_sel_hi:[1,0]
	v_pk_fma_f32 v[16:17], v[10:11], v[18:19], v[16:17]
	v_pk_mul_f32 v[14:15], v[14:15], v[74:75] op_sel_hi:[1,0]
	v_add_f32_e32 v16, v16, v17
	s_waitcnt lgkmcnt(2)
	v_pk_fma_f32 v[12:13], v[8:9], v[24:25], v[12:13]
	v_pk_fma_f32 v[14:15], v[10:11], v[26:27], v[14:15]
	v_add_f32_dpp v16, v16, v16 quad_perm:[1,0,3,2] row_mask:0xf bank_mask:0xf bound_ctrl:1
	s_nop 1
	v_add_f32_dpp v16, v16, v16 quad_perm:[2,3,0,1] row_mask:0xf bank_mask:0xf bound_ctrl:1
	s_nop 1
	v_add_f32_dpp v16, v16, v16 row_half_mirror row_mask:0xf bank_mask:0xf bound_ctrl:1
	ds_read_b128 v[84:87], v94 offset:12544
	ds_read_b128 v[80:83], v94 offset:8448
	v_add_f32_dpp v16, v16, v16 row_mirror row_mask:0xf bank_mask:0xf bound_ctrl:1
	ds_read_b32 v88, v39 offset:20736
	ds_read_b128 v[114:117], v94 offset:4352
	s_waitcnt lgkmcnt(5)
	v_pk_fma_f32 v[8:9], v[20:21], v[16:17], v[12:13] op_sel_hi:[1,0,1] neg_lo:[0,1,0] neg_hi:[0,1,0]
	v_pk_fma_f32 v[10:11], v[22:23], v[16:17], v[14:15] op_sel_hi:[1,0,1] neg_lo:[0,1,0] neg_hi:[0,1,0]
	ds_read_b128 v[110:113], v94 offset:16640
	ds_read_b128 v[118:121], v94 offset:256
	s_waitcnt lgkmcnt(5)
	v_pk_mul_f32 v[84:85], v[8:9], v[84:85]
	v_pk_mul_f32 v[28:29], v[8:9], v[28:29]
	v_pk_fma_f32 v[84:85], v[10:11], v[86:87], v[84:85]
	v_pk_fma_f32 v[28:29], v[10:11], v[30:31], v[28:29]
	v_add_f32_e32 v84, v84, v85
	s_waitcnt lgkmcnt(3)
	v_pk_mul_f32 v[80:81], v[80:81], v[88:89] op_sel_hi:[1,0]
	v_pk_mul_f32 v[82:83], v[82:83], v[88:89] op_sel_hi:[1,0]
	v_add_f32_dpp v84, v84, v84 quad_perm:[1,0,3,2] row_mask:0xf bank_mask:0xf bound_ctrl:1
	s_waitcnt lgkmcnt(2)
	v_pk_fma_f32 v[80:81], v[8:9], v[114:115], v[80:81]
	v_pk_fma_f32 v[82:83], v[10:11], v[116:117], v[82:83]
	v_add_f32_dpp v84, v84, v84 quad_perm:[2,3,0,1] row_mask:0xf bank_mask:0xf bound_ctrl:1
	v_add_f32_e32 v28, v28, v29
	ds_write_b32 v106, v28
	v_add_f32_dpp v84, v84, v84 row_half_mirror row_mask:0xf bank_mask:0xf bound_ctrl:1
	ds_read_b128 v[16:19], v94 offset:12800
	ds_read_b128 v[12:15], v94 offset:8704
	v_add_f32_dpp v84, v84, v84 row_mirror row_mask:0xf bank_mask:0xf bound_ctrl:1
	ds_read_b32 v74, v39 offset:20992
	ds_read_b128 v[24:27], v94 offset:4608
	s_waitcnt lgkmcnt(6)
	v_pk_fma_f32 v[8:9], v[110:111], v[84:85], v[80:81] op_sel_hi:[1,0,1] neg_lo:[0,1,0] neg_hi:[0,1,0]
	v_pk_fma_f32 v[10:11], v[112:113], v[84:85], v[82:83] op_sel_hi:[1,0,1] neg_lo:[0,1,0] neg_hi:[0,1,0]
	ds_read_b128 v[20:23], v94 offset:16896
	ds_read_b128 v[28:31], v94 offset:512
	s_waitcnt lgkmcnt(5)
	v_pk_mul_f32 v[16:17], v[8:9], v[16:17]
	v_pk_mul_f32 v[118:119], v[8:9], v[118:119]
	v_pk_fma_f32 v[16:17], v[10:11], v[18:19], v[16:17]
	v_pk_fma_f32 v[118:119], v[10:11], v[120:121], v[118:119]
	v_add_f32_e32 v16, v16, v17
	s_waitcnt lgkmcnt(3)
	v_pk_mul_f32 v[12:13], v[12:13], v[74:75] op_sel_hi:[1,0]
	v_pk_mul_f32 v[14:15], v[14:15], v[74:75] op_sel_hi:[1,0]
	v_add_f32_dpp v16, v16, v16 quad_perm:[1,0,3,2] row_mask:0xf bank_mask:0xf bound_ctrl:1
	s_waitcnt lgkmcnt(2)
	v_pk_fma_f32 v[12:13], v[8:9], v[24:25], v[12:13]
	v_pk_fma_f32 v[14:15], v[10:11], v[26:27], v[14:15]
	v_add_f32_dpp v16, v16, v16 quad_perm:[2,3,0,1] row_mask:0xf bank_mask:0xf bound_ctrl:1
	v_add_f32_e32 v118, v118, v119
	ds_write_b32 v106, v118 offset:1024
	v_add_f32_dpp v16, v16, v16 row_half_mirror row_mask:0xf bank_mask:0xf bound_ctrl:1
	ds_read_b128 v[84:87], v94 offset:13056
	ds_read_b128 v[80:83], v94 offset:8960
	v_add_f32_dpp v16, v16, v16 row_mirror row_mask:0xf bank_mask:0xf bound_ctrl:1
	ds_read_b32 v88, v39 offset:21248
	ds_read_b128 v[114:117], v94 offset:4864
	s_waitcnt lgkmcnt(6)
	v_pk_fma_f32 v[8:9], v[20:21], v[16:17], v[12:13] op_sel_hi:[1,0,1] neg_lo:[0,1,0] neg_hi:[0,1,0]
	v_pk_fma_f32 v[10:11], v[22:23], v[16:17], v[14:15] op_sel_hi:[1,0,1] neg_lo:[0,1,0] neg_hi:[0,1,0]
	ds_read_b128 v[110:113], v94 offset:17152
	ds_read_b128 v[118:121], v94 offset:768
	s_waitcnt lgkmcnt(5)
	v_pk_mul_f32 v[84:85], v[8:9], v[84:85]
	v_pk_mul_f32 v[28:29], v[8:9], v[28:29]
	v_pk_fma_f32 v[84:85], v[10:11], v[86:87], v[84:85]
	v_pk_fma_f32 v[28:29], v[10:11], v[30:31], v[28:29]
	v_add_f32_e32 v84, v84, v85
	s_waitcnt lgkmcnt(3)
	v_pk_mul_f32 v[80:81], v[80:81], v[88:89] op_sel_hi:[1,0]
	v_pk_mul_f32 v[82:83], v[82:83], v[88:89] op_sel_hi:[1,0]
	v_add_f32_dpp v84, v84, v84 quad_perm:[1,0,3,2] row_mask:0xf bank_mask:0xf bound_ctrl:1
	s_waitcnt lgkmcnt(2)
	v_pk_fma_f32 v[80:81], v[8:9], v[114:115], v[80:81]
	v_pk_fma_f32 v[82:83], v[10:11], v[116:117], v[82:83]
	v_add_f32_dpp v84, v84, v84 quad_perm:[2,3,0,1] row_mask:0xf bank_mask:0xf bound_ctrl:1
	v_add_f32_e32 v28, v28, v29
	ds_write_b32 v106, v28 offset:2048
	v_add_f32_dpp v84, v84, v84 row_half_mirror row_mask:0xf bank_mask:0xf bound_ctrl:1
	ds_read_b128 v[16:19], v94 offset:13312
	ds_read_b128 v[12:15], v94 offset:9216
	v_add_f32_dpp v84, v84, v84 row_mirror row_mask:0xf bank_mask:0xf bound_ctrl:1
	ds_read_b32 v74, v39 offset:21504
	ds_read_b128 v[24:27], v94 offset:5120
	s_waitcnt lgkmcnt(6)
	v_pk_fma_f32 v[8:9], v[110:111], v[84:85], v[80:81] op_sel_hi:[1,0,1] neg_lo:[0,1,0] neg_hi:[0,1,0]
	v_pk_fma_f32 v[10:11], v[112:113], v[84:85], v[82:83] op_sel_hi:[1,0,1] neg_lo:[0,1,0] neg_hi:[0,1,0]
	ds_read_b128 v[20:23], v94 offset:17408
	ds_read_b128 v[28:31], v94 offset:1024
	s_waitcnt lgkmcnt(5)
	v_pk_mul_f32 v[16:17], v[8:9], v[16:17]
	v_pk_mul_f32 v[118:119], v[8:9], v[118:119]
	v_pk_fma_f32 v[16:17], v[10:11], v[18:19], v[16:17]
	v_pk_fma_f32 v[118:119], v[10:11], v[120:121], v[118:119]
	v_add_f32_e32 v16, v16, v17
	s_waitcnt lgkmcnt(3)
	v_pk_mul_f32 v[12:13], v[12:13], v[74:75] op_sel_hi:[1,0]
	v_pk_mul_f32 v[14:15], v[14:15], v[74:75] op_sel_hi:[1,0]
	v_add_f32_dpp v16, v16, v16 quad_perm:[1,0,3,2] row_mask:0xf bank_mask:0xf bound_ctrl:1
	s_waitcnt lgkmcnt(2)
	v_pk_fma_f32 v[12:13], v[8:9], v[24:25], v[12:13]
	v_pk_fma_f32 v[14:15], v[10:11], v[26:27], v[14:15]
	v_add_f32_dpp v16, v16, v16 quad_perm:[2,3,0,1] row_mask:0xf bank_mask:0xf bound_ctrl:1
	v_add_f32_e32 v118, v118, v119
	ds_write_b32 v106, v118 offset:3072
	v_add_f32_dpp v16, v16, v16 row_half_mirror row_mask:0xf bank_mask:0xf bound_ctrl:1
	ds_read_b128 v[84:87], v94 offset:13568
	ds_read_b128 v[80:83], v94 offset:9472
	v_add_f32_dpp v16, v16, v16 row_mirror row_mask:0xf bank_mask:0xf bound_ctrl:1
	ds_read_b32 v88, v39 offset:21760
	ds_read_b128 v[114:117], v94 offset:5376
	s_waitcnt lgkmcnt(6)
	v_pk_fma_f32 v[8:9], v[20:21], v[16:17], v[12:13] op_sel_hi:[1,0,1] neg_lo:[0,1,0] neg_hi:[0,1,0]
	v_pk_fma_f32 v[10:11], v[22:23], v[16:17], v[14:15] op_sel_hi:[1,0,1] neg_lo:[0,1,0] neg_hi:[0,1,0]
	ds_read_b128 v[110:113], v94 offset:17664
	ds_read_b128 v[118:121], v94 offset:1280
	s_waitcnt lgkmcnt(5)
	v_pk_mul_f32 v[84:85], v[8:9], v[84:85]
	v_pk_mul_f32 v[28:29], v[8:9], v[28:29]
	v_pk_fma_f32 v[84:85], v[10:11], v[86:87], v[84:85]
	v_pk_fma_f32 v[28:29], v[10:11], v[30:31], v[28:29]
	v_add_f32_e32 v84, v84, v85
	s_waitcnt lgkmcnt(3)
	v_pk_mul_f32 v[80:81], v[80:81], v[88:89] op_sel_hi:[1,0]
	v_pk_mul_f32 v[82:83], v[82:83], v[88:89] op_sel_hi:[1,0]
	v_add_f32_dpp v84, v84, v84 quad_perm:[1,0,3,2] row_mask:0xf bank_mask:0xf bound_ctrl:1
	s_waitcnt lgkmcnt(2)
	v_pk_fma_f32 v[80:81], v[8:9], v[114:115], v[80:81]
	v_pk_fma_f32 v[82:83], v[10:11], v[116:117], v[82:83]
	v_add_f32_dpp v84, v84, v84 quad_perm:[2,3,0,1] row_mask:0xf bank_mask:0xf bound_ctrl:1
	v_add_f32_e32 v28, v28, v29
	ds_write_b32 v106, v28 offset:4096
	v_add_f32_dpp v84, v84, v84 row_half_mirror row_mask:0xf bank_mask:0xf bound_ctrl:1
	ds_read_b128 v[16:19], v94 offset:13824
	ds_read_b128 v[12:15], v94 offset:9728
	v_add_f32_dpp v84, v84, v84 row_mirror row_mask:0xf bank_mask:0xf bound_ctrl:1
	ds_read_b32 v74, v39 offset:22016
	ds_read_b128 v[24:27], v94 offset:5632
	s_waitcnt lgkmcnt(6)
	v_pk_fma_f32 v[8:9], v[110:111], v[84:85], v[80:81] op_sel_hi:[1,0,1] neg_lo:[0,1,0] neg_hi:[0,1,0]
	v_pk_fma_f32 v[10:11], v[112:113], v[84:85], v[82:83] op_sel_hi:[1,0,1] neg_lo:[0,1,0] neg_hi:[0,1,0]
	ds_read_b128 v[20:23], v94 offset:17920
	ds_read_b128 v[28:31], v94 offset:1536
	s_waitcnt lgkmcnt(5)
	v_pk_mul_f32 v[16:17], v[8:9], v[16:17]
	v_pk_mul_f32 v[118:119], v[8:9], v[118:119]
	v_pk_fma_f32 v[16:17], v[10:11], v[18:19], v[16:17]
	v_pk_fma_f32 v[118:119], v[10:11], v[120:121], v[118:119]
	v_add_f32_e32 v16, v16, v17
	s_waitcnt lgkmcnt(3)
	v_pk_mul_f32 v[12:13], v[12:13], v[74:75] op_sel_hi:[1,0]
	v_pk_mul_f32 v[14:15], v[14:15], v[74:75] op_sel_hi:[1,0]
	v_add_f32_dpp v16, v16, v16 quad_perm:[1,0,3,2] row_mask:0xf bank_mask:0xf bound_ctrl:1
	s_waitcnt lgkmcnt(2)
	v_pk_fma_f32 v[12:13], v[8:9], v[24:25], v[12:13]
	v_pk_fma_f32 v[14:15], v[10:11], v[26:27], v[14:15]
	v_add_f32_dpp v16, v16, v16 quad_perm:[2,3,0,1] row_mask:0xf bank_mask:0xf bound_ctrl:1
	v_add_f32_e32 v118, v118, v119
	ds_write_b32 v106, v118 offset:5120
	v_add_f32_dpp v16, v16, v16 row_half_mirror row_mask:0xf bank_mask:0xf bound_ctrl:1
	ds_read_b128 v[84:87], v94 offset:14080
	ds_read_b128 v[80:83], v94 offset:9984
	v_add_f32_dpp v16, v16, v16 row_mirror row_mask:0xf bank_mask:0xf bound_ctrl:1
	ds_read_b32 v88, v39 offset:22272
	ds_read_b128 v[114:117], v94 offset:5888
	s_waitcnt lgkmcnt(6)
	v_pk_fma_f32 v[8:9], v[20:21], v[16:17], v[12:13] op_sel_hi:[1,0,1] neg_lo:[0,1,0] neg_hi:[0,1,0]
	v_pk_fma_f32 v[10:11], v[22:23], v[16:17], v[14:15] op_sel_hi:[1,0,1] neg_lo:[0,1,0] neg_hi:[0,1,0]
	ds_read_b128 v[110:113], v94 offset:18176
	ds_read_b128 v[118:121], v94 offset:1792
	s_waitcnt lgkmcnt(5)
	v_pk_mul_f32 v[84:85], v[8:9], v[84:85]
	v_pk_mul_f32 v[28:29], v[8:9], v[28:29]
	v_pk_fma_f32 v[84:85], v[10:11], v[86:87], v[84:85]
	v_pk_fma_f32 v[28:29], v[10:11], v[30:31], v[28:29]
	v_add_f32_e32 v84, v84, v85
	s_waitcnt lgkmcnt(3)
	v_pk_mul_f32 v[80:81], v[80:81], v[88:89] op_sel_hi:[1,0]
	v_pk_mul_f32 v[82:83], v[82:83], v[88:89] op_sel_hi:[1,0]
	v_add_f32_dpp v84, v84, v84 quad_perm:[1,0,3,2] row_mask:0xf bank_mask:0xf bound_ctrl:1
	s_waitcnt lgkmcnt(2)
	v_pk_fma_f32 v[80:81], v[8:9], v[114:115], v[80:81]
	v_pk_fma_f32 v[82:83], v[10:11], v[116:117], v[82:83]
	v_add_f32_dpp v84, v84, v84 quad_perm:[2,3,0,1] row_mask:0xf bank_mask:0xf bound_ctrl:1
	v_add_f32_e32 v28, v28, v29
	ds_write_b32 v106, v28 offset:6144
	v_add_f32_dpp v84, v84, v84 row_half_mirror row_mask:0xf bank_mask:0xf bound_ctrl:1
	ds_read_b128 v[16:19], v94 offset:14336
	ds_read_b128 v[12:15], v94 offset:10240
	v_add_f32_dpp v84, v84, v84 row_mirror row_mask:0xf bank_mask:0xf bound_ctrl:1
	ds_read_b32 v74, v39 offset:22528
	ds_read_b128 v[24:27], v94 offset:6144
	s_waitcnt lgkmcnt(6)
	v_pk_fma_f32 v[8:9], v[110:111], v[84:85], v[80:81] op_sel_hi:[1,0,1] neg_lo:[0,1,0] neg_hi:[0,1,0]
	v_pk_fma_f32 v[10:11], v[112:113], v[84:85], v[82:83] op_sel_hi:[1,0,1] neg_lo:[0,1,0] neg_hi:[0,1,0]
	ds_read_b128 v[20:23], v94 offset:18432
	ds_read_b128 v[28:31], v94 offset:2048
	s_waitcnt lgkmcnt(5)
	v_pk_mul_f32 v[16:17], v[8:9], v[16:17]
	v_pk_mul_f32 v[118:119], v[8:9], v[118:119]
	v_pk_fma_f32 v[16:17], v[10:11], v[18:19], v[16:17]
	v_pk_fma_f32 v[118:119], v[10:11], v[120:121], v[118:119]
	v_add_f32_e32 v16, v16, v17
	s_waitcnt lgkmcnt(3)
	v_pk_mul_f32 v[12:13], v[12:13], v[74:75] op_sel_hi:[1,0]
	v_pk_mul_f32 v[14:15], v[14:15], v[74:75] op_sel_hi:[1,0]
	v_add_f32_dpp v16, v16, v16 quad_perm:[1,0,3,2] row_mask:0xf bank_mask:0xf bound_ctrl:1
	s_waitcnt lgkmcnt(2)
	v_pk_fma_f32 v[12:13], v[8:9], v[24:25], v[12:13]
	v_pk_fma_f32 v[14:15], v[10:11], v[26:27], v[14:15]
	v_add_f32_dpp v16, v16, v16 quad_perm:[2,3,0,1] row_mask:0xf bank_mask:0xf bound_ctrl:1
	v_add_f32_e32 v118, v118, v119
	ds_write_b32 v106, v118 offset:7168
	v_add_f32_dpp v16, v16, v16 row_half_mirror row_mask:0xf bank_mask:0xf bound_ctrl:1
	ds_read_b128 v[84:87], v94 offset:14592
	ds_read_b128 v[80:83], v94 offset:10496
	v_add_f32_dpp v16, v16, v16 row_mirror row_mask:0xf bank_mask:0xf bound_ctrl:1
	ds_read_b32 v88, v39 offset:22784
	ds_read_b128 v[114:117], v94 offset:6400
	s_waitcnt lgkmcnt(6)
	v_pk_fma_f32 v[8:9], v[20:21], v[16:17], v[12:13] op_sel_hi:[1,0,1] neg_lo:[0,1,0] neg_hi:[0,1,0]
	v_pk_fma_f32 v[10:11], v[22:23], v[16:17], v[14:15] op_sel_hi:[1,0,1] neg_lo:[0,1,0] neg_hi:[0,1,0]
	ds_read_b128 v[110:113], v94 offset:18688
	ds_read_b128 v[118:121], v94 offset:2304
	s_waitcnt lgkmcnt(5)
	v_pk_mul_f32 v[84:85], v[8:9], v[84:85]
	v_pk_mul_f32 v[28:29], v[8:9], v[28:29]
	v_pk_fma_f32 v[84:85], v[10:11], v[86:87], v[84:85]
	v_pk_fma_f32 v[28:29], v[10:11], v[30:31], v[28:29]
	v_add_f32_e32 v84, v84, v85
	s_waitcnt lgkmcnt(3)
	v_pk_mul_f32 v[80:81], v[80:81], v[88:89] op_sel_hi:[1,0]
	v_pk_mul_f32 v[82:83], v[82:83], v[88:89] op_sel_hi:[1,0]
	v_add_f32_dpp v84, v84, v84 quad_perm:[1,0,3,2] row_mask:0xf bank_mask:0xf bound_ctrl:1
	s_waitcnt lgkmcnt(2)
	v_pk_fma_f32 v[80:81], v[8:9], v[114:115], v[80:81]
	v_pk_fma_f32 v[82:83], v[10:11], v[116:117], v[82:83]
	v_add_f32_dpp v84, v84, v84 quad_perm:[2,3,0,1] row_mask:0xf bank_mask:0xf bound_ctrl:1
	v_add_f32_e32 v28, v28, v29
	ds_write_b32 v106, v28 offset:8192
	v_add_f32_dpp v84, v84, v84 row_half_mirror row_mask:0xf bank_mask:0xf bound_ctrl:1
	ds_read_b128 v[16:19], v94 offset:14848
	ds_read_b128 v[12:15], v94 offset:10752
	v_add_f32_dpp v84, v84, v84 row_mirror row_mask:0xf bank_mask:0xf bound_ctrl:1
	ds_read_b32 v74, v39 offset:23040
	ds_read_b128 v[24:27], v94 offset:6656
	s_waitcnt lgkmcnt(6)
	v_pk_fma_f32 v[8:9], v[110:111], v[84:85], v[80:81] op_sel_hi:[1,0,1] neg_lo:[0,1,0] neg_hi:[0,1,0]
	v_pk_fma_f32 v[10:11], v[112:113], v[84:85], v[82:83] op_sel_hi:[1,0,1] neg_lo:[0,1,0] neg_hi:[0,1,0]
	ds_read_b128 v[20:23], v94 offset:18944
	ds_read_b128 v[28:31], v94 offset:2560
	s_waitcnt lgkmcnt(5)
	v_pk_mul_f32 v[16:17], v[8:9], v[16:17]
	v_pk_mul_f32 v[118:119], v[8:9], v[118:119]
	v_pk_fma_f32 v[16:17], v[10:11], v[18:19], v[16:17]
	v_pk_fma_f32 v[118:119], v[10:11], v[120:121], v[118:119]
	v_add_f32_e32 v16, v16, v17
	s_waitcnt lgkmcnt(3)
	v_pk_mul_f32 v[12:13], v[12:13], v[74:75] op_sel_hi:[1,0]
	v_pk_mul_f32 v[14:15], v[14:15], v[74:75] op_sel_hi:[1,0]
	v_add_f32_dpp v16, v16, v16 quad_perm:[1,0,3,2] row_mask:0xf bank_mask:0xf bound_ctrl:1
	s_waitcnt lgkmcnt(2)
	v_pk_fma_f32 v[12:13], v[8:9], v[24:25], v[12:13]
	v_pk_fma_f32 v[14:15], v[10:11], v[26:27], v[14:15]
	v_add_f32_dpp v16, v16, v16 quad_perm:[2,3,0,1] row_mask:0xf bank_mask:0xf bound_ctrl:1
	v_add_f32_e32 v118, v118, v119
	ds_write_b32 v106, v118 offset:9216
	v_add_f32_dpp v16, v16, v16 row_half_mirror row_mask:0xf bank_mask:0xf bound_ctrl:1
	ds_read_b128 v[84:87], v94 offset:15104
	ds_read_b128 v[80:83], v94 offset:11008
	v_add_f32_dpp v16, v16, v16 row_mirror row_mask:0xf bank_mask:0xf bound_ctrl:1
	ds_read_b32 v88, v39 offset:23296
	ds_read_b128 v[114:117], v94 offset:6912
	s_waitcnt lgkmcnt(6)
	v_pk_fma_f32 v[8:9], v[20:21], v[16:17], v[12:13] op_sel_hi:[1,0,1] neg_lo:[0,1,0] neg_hi:[0,1,0]
	v_pk_fma_f32 v[10:11], v[22:23], v[16:17], v[14:15] op_sel_hi:[1,0,1] neg_lo:[0,1,0] neg_hi:[0,1,0]
	ds_read_b128 v[110:113], v94 offset:19200
	ds_read_b128 v[118:121], v94 offset:2816
	s_waitcnt lgkmcnt(5)
	v_pk_mul_f32 v[84:85], v[8:9], v[84:85]
	v_pk_mul_f32 v[28:29], v[8:9], v[28:29]
	v_pk_fma_f32 v[84:85], v[10:11], v[86:87], v[84:85]
	v_pk_fma_f32 v[28:29], v[10:11], v[30:31], v[28:29]
	v_add_f32_e32 v84, v84, v85
	s_waitcnt lgkmcnt(3)
	v_pk_mul_f32 v[80:81], v[80:81], v[88:89] op_sel_hi:[1,0]
	v_pk_mul_f32 v[82:83], v[82:83], v[88:89] op_sel_hi:[1,0]
	v_add_f32_dpp v84, v84, v84 quad_perm:[1,0,3,2] row_mask:0xf bank_mask:0xf bound_ctrl:1
	s_waitcnt lgkmcnt(2)
	v_pk_fma_f32 v[80:81], v[8:9], v[114:115], v[80:81]
	v_pk_fma_f32 v[82:83], v[10:11], v[116:117], v[82:83]
	v_add_f32_dpp v84, v84, v84 quad_perm:[2,3,0,1] row_mask:0xf bank_mask:0xf bound_ctrl:1
	v_add_f32_e32 v28, v28, v29
	ds_write_b32 v106, v28 offset:10240
	v_add_f32_dpp v84, v84, v84 row_half_mirror row_mask:0xf bank_mask:0xf bound_ctrl:1
	ds_read_b128 v[16:19], v94 offset:15360
	ds_read_b128 v[12:15], v94 offset:11264
	v_add_f32_dpp v84, v84, v84 row_mirror row_mask:0xf bank_mask:0xf bound_ctrl:1
	ds_read_b32 v74, v39 offset:23552
	ds_read_b128 v[24:27], v94 offset:7168
	s_waitcnt lgkmcnt(6)
	v_pk_fma_f32 v[8:9], v[110:111], v[84:85], v[80:81] op_sel_hi:[1,0,1] neg_lo:[0,1,0] neg_hi:[0,1,0]
	v_pk_fma_f32 v[10:11], v[112:113], v[84:85], v[82:83] op_sel_hi:[1,0,1] neg_lo:[0,1,0] neg_hi:[0,1,0]
	ds_read_b128 v[20:23], v94 offset:19456
	ds_read_b128 v[28:31], v94 offset:3072
	s_waitcnt lgkmcnt(5)
	v_pk_mul_f32 v[16:17], v[8:9], v[16:17]
	v_pk_mul_f32 v[118:119], v[8:9], v[118:119]
	v_pk_fma_f32 v[16:17], v[10:11], v[18:19], v[16:17]
	v_pk_fma_f32 v[118:119], v[10:11], v[120:121], v[118:119]
	v_add_f32_e32 v16, v16, v17
	s_waitcnt lgkmcnt(3)
	v_pk_mul_f32 v[12:13], v[12:13], v[74:75] op_sel_hi:[1,0]
	v_pk_mul_f32 v[14:15], v[14:15], v[74:75] op_sel_hi:[1,0]
	v_add_f32_dpp v16, v16, v16 quad_perm:[1,0,3,2] row_mask:0xf bank_mask:0xf bound_ctrl:1
	s_waitcnt lgkmcnt(2)
	v_pk_fma_f32 v[12:13], v[8:9], v[24:25], v[12:13]
	v_pk_fma_f32 v[14:15], v[10:11], v[26:27], v[14:15]
	v_add_f32_dpp v16, v16, v16 quad_perm:[2,3,0,1] row_mask:0xf bank_mask:0xf bound_ctrl:1
	v_add_f32_e32 v118, v118, v119
	ds_write_b32 v106, v118 offset:11264
	v_add_f32_dpp v16, v16, v16 row_half_mirror row_mask:0xf bank_mask:0xf bound_ctrl:1
	ds_read_b128 v[84:87], v94 offset:15616
	ds_read_b128 v[80:83], v94 offset:11520
	v_add_f32_dpp v16, v16, v16 row_mirror row_mask:0xf bank_mask:0xf bound_ctrl:1
	ds_read_b32 v88, v39 offset:23808
	ds_read_b128 v[114:117], v94 offset:7424
	s_waitcnt lgkmcnt(6)
	v_pk_fma_f32 v[8:9], v[20:21], v[16:17], v[12:13] op_sel_hi:[1,0,1] neg_lo:[0,1,0] neg_hi:[0,1,0]
	v_pk_fma_f32 v[10:11], v[22:23], v[16:17], v[14:15] op_sel_hi:[1,0,1] neg_lo:[0,1,0] neg_hi:[0,1,0]
	ds_read_b128 v[110:113], v94 offset:19712
	ds_read_b128 v[118:121], v94 offset:3328
	s_waitcnt lgkmcnt(5)
	v_pk_mul_f32 v[84:85], v[8:9], v[84:85]
	v_pk_mul_f32 v[28:29], v[8:9], v[28:29]
	v_pk_fma_f32 v[84:85], v[10:11], v[86:87], v[84:85]
	v_pk_fma_f32 v[28:29], v[10:11], v[30:31], v[28:29]
	v_add_f32_e32 v84, v84, v85
	s_waitcnt lgkmcnt(3)
	v_pk_mul_f32 v[80:81], v[80:81], v[88:89] op_sel_hi:[1,0]
	v_pk_mul_f32 v[82:83], v[82:83], v[88:89] op_sel_hi:[1,0]
	v_add_f32_dpp v84, v84, v84 quad_perm:[1,0,3,2] row_mask:0xf bank_mask:0xf bound_ctrl:1
	s_waitcnt lgkmcnt(2)
	v_pk_fma_f32 v[80:81], v[8:9], v[114:115], v[80:81]
	v_pk_fma_f32 v[82:83], v[10:11], v[116:117], v[82:83]
	v_add_f32_dpp v84, v84, v84 quad_perm:[2,3,0,1] row_mask:0xf bank_mask:0xf bound_ctrl:1
	v_add_f32_e32 v28, v28, v29
	ds_write_b32 v106, v28 offset:12288
	v_add_f32_dpp v84, v84, v84 row_half_mirror row_mask:0xf bank_mask:0xf bound_ctrl:1
	ds_read_b128 v[16:19], v94 offset:15872
	ds_read_b128 v[12:15], v94 offset:11776
	v_add_f32_dpp v84, v84, v84 row_mirror row_mask:0xf bank_mask:0xf bound_ctrl:1
	ds_read_b32 v74, v39 offset:24064
	ds_read_b128 v[24:27], v94 offset:7680
	s_waitcnt lgkmcnt(6)
	v_pk_fma_f32 v[8:9], v[110:111], v[84:85], v[80:81] op_sel_hi:[1,0,1] neg_lo:[0,1,0] neg_hi:[0,1,0]
	v_pk_fma_f32 v[10:11], v[112:113], v[84:85], v[82:83] op_sel_hi:[1,0,1] neg_lo:[0,1,0] neg_hi:[0,1,0]
	ds_read_b128 v[20:23], v94 offset:19968
	ds_read_b128 v[28:31], v94 offset:3584
	s_waitcnt lgkmcnt(5)
	v_pk_mul_f32 v[16:17], v[8:9], v[16:17]
	v_pk_mul_f32 v[118:119], v[8:9], v[118:119]
	v_pk_fma_f32 v[16:17], v[10:11], v[18:19], v[16:17]
	v_pk_fma_f32 v[118:119], v[10:11], v[120:121], v[118:119]
	v_add_f32_e32 v16, v16, v17
	s_waitcnt lgkmcnt(3)
	v_pk_mul_f32 v[12:13], v[12:13], v[74:75] op_sel_hi:[1,0]
	v_pk_mul_f32 v[14:15], v[14:15], v[74:75] op_sel_hi:[1,0]
	v_add_f32_dpp v16, v16, v16 quad_perm:[1,0,3,2] row_mask:0xf bank_mask:0xf bound_ctrl:1
	s_waitcnt lgkmcnt(2)
	v_pk_fma_f32 v[12:13], v[8:9], v[24:25], v[12:13]
	v_pk_fma_f32 v[14:15], v[10:11], v[26:27], v[14:15]
	v_add_f32_dpp v16, v16, v16 quad_perm:[2,3,0,1] row_mask:0xf bank_mask:0xf bound_ctrl:1
	v_add_f32_e32 v118, v118, v119
	ds_write_b32 v106, v118 offset:13312
	v_add_f32_dpp v16, v16, v16 row_half_mirror row_mask:0xf bank_mask:0xf bound_ctrl:1
	ds_read_b128 v[84:87], v94 offset:16128
	ds_read_b128 v[80:83], v94 offset:12032
	v_add_f32_dpp v16, v16, v16 row_mirror row_mask:0xf bank_mask:0xf bound_ctrl:1
	ds_read_b32 v88, v39 offset:24320
	ds_read_b128 v[114:117], v94 offset:7936
	s_waitcnt lgkmcnt(6)
	v_pk_fma_f32 v[8:9], v[20:21], v[16:17], v[12:13] op_sel_hi:[1,0,1] neg_lo:[0,1,0] neg_hi:[0,1,0]
	v_pk_fma_f32 v[10:11], v[22:23], v[16:17], v[14:15] op_sel_hi:[1,0,1] neg_lo:[0,1,0] neg_hi:[0,1,0]
	ds_read_b128 v[110:113], v94 offset:20224
	ds_read_b128 v[118:121], v94 offset:3840
	s_waitcnt lgkmcnt(5)
	v_pk_mul_f32 v[84:85], v[8:9], v[84:85]
	v_pk_mul_f32 v[28:29], v[8:9], v[28:29]
	v_pk_fma_f32 v[84:85], v[10:11], v[86:87], v[84:85]
	v_pk_fma_f32 v[28:29], v[10:11], v[30:31], v[28:29]
	v_add_f32_e32 v84, v84, v85
	s_waitcnt lgkmcnt(3)
	v_pk_mul_f32 v[80:81], v[80:81], v[88:89] op_sel_hi:[1,0]
	v_pk_mul_f32 v[82:83], v[82:83], v[88:89] op_sel_hi:[1,0]
	v_add_f32_dpp v84, v84, v84 quad_perm:[1,0,3,2] row_mask:0xf bank_mask:0xf bound_ctrl:1
	s_waitcnt lgkmcnt(2)
	v_pk_fma_f32 v[80:81], v[8:9], v[114:115], v[80:81]
	v_pk_fma_f32 v[82:83], v[10:11], v[116:117], v[82:83]
	v_add_f32_dpp v84, v84, v84 quad_perm:[2,3,0,1] row_mask:0xf bank_mask:0xf bound_ctrl:1
	v_add_f32_e32 v28, v28, v29
	ds_write_b32 v106, v28 offset:14336
	v_add_f32_dpp v84, v84, v84 row_half_mirror row_mask:0xf bank_mask:0xf bound_ctrl:1
	s_nop 1
	v_add_f32_dpp v84, v84, v84 row_mirror row_mask:0xf bank_mask:0xf bound_ctrl:1
	s_waitcnt lgkmcnt(2)
	v_pk_fma_f32 v[8:9], v[110:111], v[84:85], v[80:81] op_sel_hi:[1,0,1] neg_lo:[0,1,0] neg_hi:[0,1,0]
	v_pk_fma_f32 v[10:11], v[112:113], v[84:85], v[82:83] op_sel_hi:[1,0,1] neg_lo:[0,1,0] neg_hi:[0,1,0]
	s_waitcnt lgkmcnt(1)
	v_pk_mul_f32 v[118:119], v[8:9], v[118:119]
	s_nop 0
	v_pk_fma_f32 v[118:119], v[10:11], v[120:121], v[118:119]
	s_nop 0
	v_add_f32_e32 v118, v118, v119
	ds_write_b32 v106, v118 offset:15360
	s_waitcnt lgkmcnt(0)
	s_barrier
	ds_read_b128 v[12:15], v107 offset:24576
	ds_read_b128 v[16:19], v107 offset:24592
	ds_read_b128 v[20:23], v107 offset:24608
	ds_read_b128 v[24:27], v107 offset:24624
	s_or_b32 s89, s88, 1
	s_waitcnt lgkmcnt(3)
	v_mov_b32_e32 v28, v13
	v_mov_b32_e32 v29, v14
	s_waitcnt lgkmcnt(2)
	v_mov_b32_e32 v30, v17
	v_mov_b32_e32 v31, v18
	v_mov_b32_e32 v13, v15
	v_mov_b32_e32 v17, v19
	v_pk_add_f32 v[12:13], v[28:29], v[12:13]
	v_pk_add_f32 v[14:15], v[30:31], v[16:17]
	s_waitcnt lgkmcnt(1)
	v_mov_b32_e32 v16, v21
	v_mov_b32_e32 v18, v23
	v_pk_add_f32 v[12:13], v[12:13], v[12:13] op_sel:[0,1] op_sel_hi:[1,0]
	v_pk_add_f32 v[14:15], v[14:15], v[14:15] op_sel:[0,1] op_sel_hi:[1,0]
	v_pk_add_f32 v[16:17], v[20:21], v[16:17]
	v_pk_add_f32 v[18:19], v[22:23], v[18:19]
	s_waitcnt lgkmcnt(0)
	v_mov_b32_e32 v13, v24
	v_mov_b32_e32 v15, v25
	v_mov_b32_e32 v17, v26
	v_mov_b32_e32 v19, v27
	v_pk_add_f32 v[12:13], v[12:13], v[14:15]
	v_pk_add_f32 v[14:15], v[16:17], v[18:19]
	v_cmp_lt_u32_e32 vcc, s89, v75
	v_pk_add_f32 v[12:13], v[12:13], v[14:15]
	s_nop 0
	v_pk_add_f32 v[12:13], v[12:13], v[12:13] op_sel:[0,1] op_sel_hi:[1,0]
	s_nop 0
	v_bfe_u32 v13, v12, 16, 1
	v_add3_u32 v14, v12, v13, s33
	v_lshl_add_u32 v12, s88, 4, v38
	v_ashrrev_i32_e32 v13, 31, v12
	v_lshlrev_b64 v[12:13], 11, v[12:13]
	v_lshl_add_u64 v[12:13], v[50:51], 0, v[12:13]
	global_store_short_d16_hi v[12:13], v14, off
	s_and_saveexec_b64 s[0:1], vcc
	s_cbranch_execz .LBB0_200
	s_waitcnt vmcnt(1)
	v_and_b32_e32 v13, 0xffff0000, v56
	v_lshlrev_b32_e32 v12, 16, v56
	v_and_b32_e32 v15, 0xffff0000, v57
	v_lshlrev_b32_e32 v14, 16, v57
	ds_write_b128 v103, v[12:15]
	v_and_b32_e32 v13, 0xffff0000, v58
	v_lshlrev_b32_e32 v12, 16, v58
	v_and_b32_e32 v15, 0xffff0000, v59
	v_lshlrev_b32_e32 v14, 16, v59
	ds_write_b128 v103, v[12:15] offset:8192
	v_and_b32_e32 v13, 0xffff0000, v60
	v_lshlrev_b32_e32 v12, 16, v60
	v_and_b32_e32 v15, 0xffff0000, v61
	v_lshlrev_b32_e32 v14, 16, v61
	ds_write_b128 v103, v[12:15] offset:12288
	v_and_b32_e32 v13, 0xffff0000, v62
	v_lshlrev_b32_e32 v12, 16, v62
	v_and_b32_e32 v15, 0xffff0000, v63
	v_lshlrev_b32_e32 v14, 16, v63
	s_add_i32 s88, s88, 3
	ds_write_b128 v103, v[12:15] offset:16384
	v_and_b32_e32 v13, 0xffff0000, v54
	v_lshlrev_b32_e32 v12, 16, v54
	v_and_b32_e32 v15, 0xffff0000, v55
	v_lshlrev_b32_e32 v14, 16, v55
	v_cmp_lt_u32_e32 vcc, s88, v75
	ds_write_b128 v103, v[12:15] offset:20480
	ds_write_b128 v103, v[4:7] offset:4096
	s_waitcnt lgkmcnt(0)
	s_barrier
	s_and_saveexec_b64 s[6:7], vcc
	s_cbranch_execz .LBB0_208
	v_lshl_add_u32 v4, s88, 4, v38
	v_ashrrev_i32_e32 v5, 31, v4
	v_lshlrev_b64 v[4:5], 10, v[4:5]
	v_or_b32_e32 v5, v5, v35
	v_or_b32_e32 v4, v4, v52
	v_lshlrev_b64 v[6:7], 1, v[4:5]
	v_lshl_add_u64 v[12:13], s[8:9], 0, v[6:7]
	v_lshl_add_u64 v[14:15], s[10:11], 0, v[6:7]
	v_lshl_add_u64 v[16:17], s[12:13], 0, v[6:7]
	v_lshl_add_u64 v[18:19], s[14:15], 0, v[6:7]
	global_load_dwordx2 v[56:57], v[12:13], off
	global_load_dwordx2 v[58:59], v[14:15], off
	global_load_dwordx2 v[60:61], v[16:17], off
	global_load_dwordx2 v[62:63], v[18:19], off
	v_lshl_add_u64 v[6:7], s[34:35], 0, v[6:7]
	v_lshl_add_u64 v[4:5], v[4:5], 2, s[36:37]
	global_load_dwordx2 v[54:55], v[6:7], off
	s_nop 0
	global_load_dwordx4 v[4:7], v[4:5], off
.LBB0_208:
	s_or_b64 exec, exec, s[6:7]
	ds_read_b128 v[16:19], v94 offset:12288
	ds_read_b128 v[12:15], v94 offset:8192
	ds_read_b32 v74, v39 offset:20480
	ds_read_b128 v[24:27], v94 offset:4096
	ds_read_b128 v[20:23], v94 offset:16384
	ds_read_b128 v[28:31], v94 offset:0
	s_waitcnt lgkmcnt(3)
	v_pk_mul_f32 v[16:17], v[8:9], v[16:17]
	v_pk_mul_f32 v[12:13], v[12:13], v[74:75] op_sel_hi:[1,0]
	v_pk_fma_f32 v[16:17], v[10:11], v[18:19], v[16:17]
	v_pk_mul_f32 v[14:15], v[14:15], v[74:75] op_sel_hi:[1,0]
	v_add_f32_e32 v16, v16, v17
	s_waitcnt lgkmcnt(2)
	v_pk_fma_f32 v[12:13], v[8:9], v[24:25], v[12:13]
	v_pk_fma_f32 v[14:15], v[10:11], v[26:27], v[14:15]
	v_add_f32_dpp v16, v16, v16 quad_perm:[1,0,3,2] row_mask:0xf bank_mask:0xf bound_ctrl:1
	s_nop 1
	v_add_f32_dpp v16, v16, v16 quad_perm:[2,3,0,1] row_mask:0xf bank_mask:0xf bound_ctrl:1
	s_nop 1
	v_add_f32_dpp v16, v16, v16 row_half_mirror row_mask:0xf bank_mask:0xf bound_ctrl:1
	ds_read_b128 v[84:87], v94 offset:12544
	ds_read_b128 v[80:83], v94 offset:8448
	v_add_f32_dpp v16, v16, v16 row_mirror row_mask:0xf bank_mask:0xf bound_ctrl:1
	ds_read_b32 v88, v39 offset:20736
	ds_read_b128 v[114:117], v94 offset:4352
	s_waitcnt lgkmcnt(5)
	v_pk_fma_f32 v[8:9], v[20:21], v[16:17], v[12:13] op_sel_hi:[1,0,1] neg_lo:[0,1,0] neg_hi:[0,1,0]
	v_pk_fma_f32 v[10:11], v[22:23], v[16:17], v[14:15] op_sel_hi:[1,0,1] neg_lo:[0,1,0] neg_hi:[0,1,0]
	ds_read_b128 v[110:113], v94 offset:16640
	ds_read_b128 v[118:121], v94 offset:256
	s_waitcnt lgkmcnt(5)
	v_pk_mul_f32 v[84:85], v[8:9], v[84:85]
	v_pk_mul_f32 v[28:29], v[8:9], v[28:29]
	v_pk_fma_f32 v[84:85], v[10:11], v[86:87], v[84:85]
	v_pk_fma_f32 v[28:29], v[10:11], v[30:31], v[28:29]
	v_add_f32_e32 v84, v84, v85
	s_waitcnt lgkmcnt(3)
	v_pk_mul_f32 v[80:81], v[80:81], v[88:89] op_sel_hi:[1,0]
	v_pk_mul_f32 v[82:83], v[82:83], v[88:89] op_sel_hi:[1,0]
	v_add_f32_dpp v84, v84, v84 quad_perm:[1,0,3,2] row_mask:0xf bank_mask:0xf bound_ctrl:1
	s_waitcnt lgkmcnt(2)
	v_pk_fma_f32 v[80:81], v[8:9], v[114:115], v[80:81]
	v_pk_fma_f32 v[82:83], v[10:11], v[116:117], v[82:83]
	v_add_f32_dpp v84, v84, v84 quad_perm:[2,3,0,1] row_mask:0xf bank_mask:0xf bound_ctrl:1
	v_add_f32_e32 v28, v28, v29
	ds_write_b32 v106, v28
	v_add_f32_dpp v84, v84, v84 row_half_mirror row_mask:0xf bank_mask:0xf bound_ctrl:1
	ds_read_b128 v[16:19], v94 offset:12800
	ds_read_b128 v[12:15], v94 offset:8704
	v_add_f32_dpp v84, v84, v84 row_mirror row_mask:0xf bank_mask:0xf bound_ctrl:1
	ds_read_b32 v74, v39 offset:20992
	ds_read_b128 v[24:27], v94 offset:4608
	s_waitcnt lgkmcnt(6)
	v_pk_fma_f32 v[8:9], v[110:111], v[84:85], v[80:81] op_sel_hi:[1,0,1] neg_lo:[0,1,0] neg_hi:[0,1,0]
	v_pk_fma_f32 v[10:11], v[112:113], v[84:85], v[82:83] op_sel_hi:[1,0,1] neg_lo:[0,1,0] neg_hi:[0,1,0]
	ds_read_b128 v[20:23], v94 offset:16896
	ds_read_b128 v[28:31], v94 offset:512
	s_waitcnt lgkmcnt(5)
	v_pk_mul_f32 v[16:17], v[8:9], v[16:17]
	v_pk_mul_f32 v[118:119], v[8:9], v[118:119]
	v_pk_fma_f32 v[16:17], v[10:11], v[18:19], v[16:17]
	v_pk_fma_f32 v[118:119], v[10:11], v[120:121], v[118:119]
	v_add_f32_e32 v16, v16, v17
	s_waitcnt lgkmcnt(3)
	v_pk_mul_f32 v[12:13], v[12:13], v[74:75] op_sel_hi:[1,0]
	v_pk_mul_f32 v[14:15], v[14:15], v[74:75] op_sel_hi:[1,0]
	v_add_f32_dpp v16, v16, v16 quad_perm:[1,0,3,2] row_mask:0xf bank_mask:0xf bound_ctrl:1
	s_waitcnt lgkmcnt(2)
	v_pk_fma_f32 v[12:13], v[8:9], v[24:25], v[12:13]
	v_pk_fma_f32 v[14:15], v[10:11], v[26:27], v[14:15]
	v_add_f32_dpp v16, v16, v16 quad_perm:[2,3,0,1] row_mask:0xf bank_mask:0xf bound_ctrl:1
	v_add_f32_e32 v118, v118, v119
	ds_write_b32 v106, v118 offset:1024
	v_add_f32_dpp v16, v16, v16 row_half_mirror row_mask:0xf bank_mask:0xf bound_ctrl:1
	ds_read_b128 v[84:87], v94 offset:13056
	ds_read_b128 v[80:83], v94 offset:8960
	v_add_f32_dpp v16, v16, v16 row_mirror row_mask:0xf bank_mask:0xf bound_ctrl:1
	ds_read_b32 v88, v39 offset:21248
	ds_read_b128 v[114:117], v94 offset:4864
	s_waitcnt lgkmcnt(6)
	v_pk_fma_f32 v[8:9], v[20:21], v[16:17], v[12:13] op_sel_hi:[1,0,1] neg_lo:[0,1,0] neg_hi:[0,1,0]
	v_pk_fma_f32 v[10:11], v[22:23], v[16:17], v[14:15] op_sel_hi:[1,0,1] neg_lo:[0,1,0] neg_hi:[0,1,0]
	ds_read_b128 v[110:113], v94 offset:17152
	ds_read_b128 v[118:121], v94 offset:768
	s_waitcnt lgkmcnt(5)
	v_pk_mul_f32 v[84:85], v[8:9], v[84:85]
	v_pk_mul_f32 v[28:29], v[8:9], v[28:29]
	v_pk_fma_f32 v[84:85], v[10:11], v[86:87], v[84:85]
	v_pk_fma_f32 v[28:29], v[10:11], v[30:31], v[28:29]
	v_add_f32_e32 v84, v84, v85
	s_waitcnt lgkmcnt(3)
	v_pk_mul_f32 v[80:81], v[80:81], v[88:89] op_sel_hi:[1,0]
	v_pk_mul_f32 v[82:83], v[82:83], v[88:89] op_sel_hi:[1,0]
	v_add_f32_dpp v84, v84, v84 quad_perm:[1,0,3,2] row_mask:0xf bank_mask:0xf bound_ctrl:1
	s_waitcnt lgkmcnt(2)
	v_pk_fma_f32 v[80:81], v[8:9], v[114:115], v[80:81]
	v_pk_fma_f32 v[82:83], v[10:11], v[116:117], v[82:83]
	v_add_f32_dpp v84, v84, v84 quad_perm:[2,3,0,1] row_mask:0xf bank_mask:0xf bound_ctrl:1
	v_add_f32_e32 v28, v28, v29
	ds_write_b32 v106, v28 offset:2048
	v_add_f32_dpp v84, v84, v84 row_half_mirror row_mask:0xf bank_mask:0xf bound_ctrl:1
	ds_read_b128 v[16:19], v94 offset:13312
	ds_read_b128 v[12:15], v94 offset:9216
	v_add_f32_dpp v84, v84, v84 row_mirror row_mask:0xf bank_mask:0xf bound_ctrl:1
	ds_read_b32 v74, v39 offset:21504
	ds_read_b128 v[24:27], v94 offset:5120
	s_waitcnt lgkmcnt(6)
	v_pk_fma_f32 v[8:9], v[110:111], v[84:85], v[80:81] op_sel_hi:[1,0,1] neg_lo:[0,1,0] neg_hi:[0,1,0]
	v_pk_fma_f32 v[10:11], v[112:113], v[84:85], v[82:83] op_sel_hi:[1,0,1] neg_lo:[0,1,0] neg_hi:[0,1,0]
	ds_read_b128 v[20:23], v94 offset:17408
	ds_read_b128 v[28:31], v94 offset:1024
	s_waitcnt lgkmcnt(5)
	v_pk_mul_f32 v[16:17], v[8:9], v[16:17]
	v_pk_mul_f32 v[118:119], v[8:9], v[118:119]
	v_pk_fma_f32 v[16:17], v[10:11], v[18:19], v[16:17]
	v_pk_fma_f32 v[118:119], v[10:11], v[120:121], v[118:119]
	v_add_f32_e32 v16, v16, v17
	s_waitcnt lgkmcnt(3)
	v_pk_mul_f32 v[12:13], v[12:13], v[74:75] op_sel_hi:[1,0]
	v_pk_mul_f32 v[14:15], v[14:15], v[74:75] op_sel_hi:[1,0]
	v_add_f32_dpp v16, v16, v16 quad_perm:[1,0,3,2] row_mask:0xf bank_mask:0xf bound_ctrl:1
	s_waitcnt lgkmcnt(2)
	v_pk_fma_f32 v[12:13], v[8:9], v[24:25], v[12:13]
	v_pk_fma_f32 v[14:15], v[10:11], v[26:27], v[14:15]
	v_add_f32_dpp v16, v16, v16 quad_perm:[2,3,0,1] row_mask:0xf bank_mask:0xf bound_ctrl:1
	v_add_f32_e32 v118, v118, v119
	ds_write_b32 v106, v118 offset:3072
	v_add_f32_dpp v16, v16, v16 row_half_mirror row_mask:0xf bank_mask:0xf bound_ctrl:1
	ds_read_b128 v[84:87], v94 offset:13568
	ds_read_b128 v[80:83], v94 offset:9472
	v_add_f32_dpp v16, v16, v16 row_mirror row_mask:0xf bank_mask:0xf bound_ctrl:1
	ds_read_b32 v88, v39 offset:21760
	ds_read_b128 v[114:117], v94 offset:5376
	s_waitcnt lgkmcnt(6)
	v_pk_fma_f32 v[8:9], v[20:21], v[16:17], v[12:13] op_sel_hi:[1,0,1] neg_lo:[0,1,0] neg_hi:[0,1,0]
	v_pk_fma_f32 v[10:11], v[22:23], v[16:17], v[14:15] op_sel_hi:[1,0,1] neg_lo:[0,1,0] neg_hi:[0,1,0]
	ds_read_b128 v[110:113], v94 offset:17664
	ds_read_b128 v[118:121], v94 offset:1280
	s_waitcnt lgkmcnt(5)
	v_pk_mul_f32 v[84:85], v[8:9], v[84:85]
	v_pk_mul_f32 v[28:29], v[8:9], v[28:29]
	v_pk_fma_f32 v[84:85], v[10:11], v[86:87], v[84:85]
	v_pk_fma_f32 v[28:29], v[10:11], v[30:31], v[28:29]
	v_add_f32_e32 v84, v84, v85
	s_waitcnt lgkmcnt(3)
	v_pk_mul_f32 v[80:81], v[80:81], v[88:89] op_sel_hi:[1,0]
	v_pk_mul_f32 v[82:83], v[82:83], v[88:89] op_sel_hi:[1,0]
	v_add_f32_dpp v84, v84, v84 quad_perm:[1,0,3,2] row_mask:0xf bank_mask:0xf bound_ctrl:1
	s_waitcnt lgkmcnt(2)
	v_pk_fma_f32 v[80:81], v[8:9], v[114:115], v[80:81]
	v_pk_fma_f32 v[82:83], v[10:11], v[116:117], v[82:83]
	v_add_f32_dpp v84, v84, v84 quad_perm:[2,3,0,1] row_mask:0xf bank_mask:0xf bound_ctrl:1
	v_add_f32_e32 v28, v28, v29
	ds_write_b32 v106, v28 offset:4096
	v_add_f32_dpp v84, v84, v84 row_half_mirror row_mask:0xf bank_mask:0xf bound_ctrl:1
	ds_read_b128 v[16:19], v94 offset:13824
	ds_read_b128 v[12:15], v94 offset:9728
	v_add_f32_dpp v84, v84, v84 row_mirror row_mask:0xf bank_mask:0xf bound_ctrl:1
	ds_read_b32 v74, v39 offset:22016
	ds_read_b128 v[24:27], v94 offset:5632
	s_waitcnt lgkmcnt(6)
	v_pk_fma_f32 v[8:9], v[110:111], v[84:85], v[80:81] op_sel_hi:[1,0,1] neg_lo:[0,1,0] neg_hi:[0,1,0]
	v_pk_fma_f32 v[10:11], v[112:113], v[84:85], v[82:83] op_sel_hi:[1,0,1] neg_lo:[0,1,0] neg_hi:[0,1,0]
	ds_read_b128 v[20:23], v94 offset:17920
	ds_read_b128 v[28:31], v94 offset:1536
	s_waitcnt lgkmcnt(5)
	v_pk_mul_f32 v[16:17], v[8:9], v[16:17]
	v_pk_mul_f32 v[118:119], v[8:9], v[118:119]
	v_pk_fma_f32 v[16:17], v[10:11], v[18:19], v[16:17]
	v_pk_fma_f32 v[118:119], v[10:11], v[120:121], v[118:119]
	v_add_f32_e32 v16, v16, v17
	s_waitcnt lgkmcnt(3)
	v_pk_mul_f32 v[12:13], v[12:13], v[74:75] op_sel_hi:[1,0]
	v_pk_mul_f32 v[14:15], v[14:15], v[74:75] op_sel_hi:[1,0]
	v_add_f32_dpp v16, v16, v16 quad_perm:[1,0,3,2] row_mask:0xf bank_mask:0xf bound_ctrl:1
	s_waitcnt lgkmcnt(2)
	v_pk_fma_f32 v[12:13], v[8:9], v[24:25], v[12:13]
	v_pk_fma_f32 v[14:15], v[10:11], v[26:27], v[14:15]
	v_add_f32_dpp v16, v16, v16 quad_perm:[2,3,0,1] row_mask:0xf bank_mask:0xf bound_ctrl:1
	v_add_f32_e32 v118, v118, v119
	ds_write_b32 v106, v118 offset:5120
	v_add_f32_dpp v16, v16, v16 row_half_mirror row_mask:0xf bank_mask:0xf bound_ctrl:1
	ds_read_b128 v[84:87], v94 offset:14080
	ds_read_b128 v[80:83], v94 offset:9984
	v_add_f32_dpp v16, v16, v16 row_mirror row_mask:0xf bank_mask:0xf bound_ctrl:1
	ds_read_b32 v88, v39 offset:22272
	ds_read_b128 v[114:117], v94 offset:5888
	s_waitcnt lgkmcnt(6)
	v_pk_fma_f32 v[8:9], v[20:21], v[16:17], v[12:13] op_sel_hi:[1,0,1] neg_lo:[0,1,0] neg_hi:[0,1,0]
	v_pk_fma_f32 v[10:11], v[22:23], v[16:17], v[14:15] op_sel_hi:[1,0,1] neg_lo:[0,1,0] neg_hi:[0,1,0]
	ds_read_b128 v[110:113], v94 offset:18176
	ds_read_b128 v[118:121], v94 offset:1792
	s_waitcnt lgkmcnt(5)
	v_pk_mul_f32 v[84:85], v[8:9], v[84:85]
	v_pk_mul_f32 v[28:29], v[8:9], v[28:29]
	v_pk_fma_f32 v[84:85], v[10:11], v[86:87], v[84:85]
	v_pk_fma_f32 v[28:29], v[10:11], v[30:31], v[28:29]
	v_add_f32_e32 v84, v84, v85
	s_waitcnt lgkmcnt(3)
	v_pk_mul_f32 v[80:81], v[80:81], v[88:89] op_sel_hi:[1,0]
	v_pk_mul_f32 v[82:83], v[82:83], v[88:89] op_sel_hi:[1,0]
	v_add_f32_dpp v84, v84, v84 quad_perm:[1,0,3,2] row_mask:0xf bank_mask:0xf bound_ctrl:1
	s_waitcnt lgkmcnt(2)
	v_pk_fma_f32 v[80:81], v[8:9], v[114:115], v[80:81]
	v_pk_fma_f32 v[82:83], v[10:11], v[116:117], v[82:83]
	v_add_f32_dpp v84, v84, v84 quad_perm:[2,3,0,1] row_mask:0xf bank_mask:0xf bound_ctrl:1
	v_add_f32_e32 v28, v28, v29
	ds_write_b32 v106, v28 offset:6144
	v_add_f32_dpp v84, v84, v84 row_half_mirror row_mask:0xf bank_mask:0xf bound_ctrl:1
	ds_read_b128 v[16:19], v94 offset:14336
	ds_read_b128 v[12:15], v94 offset:10240
	v_add_f32_dpp v84, v84, v84 row_mirror row_mask:0xf bank_mask:0xf bound_ctrl:1
	ds_read_b32 v74, v39 offset:22528
	ds_read_b128 v[24:27], v94 offset:6144
	s_waitcnt lgkmcnt(6)
	v_pk_fma_f32 v[8:9], v[110:111], v[84:85], v[80:81] op_sel_hi:[1,0,1] neg_lo:[0,1,0] neg_hi:[0,1,0]
	v_pk_fma_f32 v[10:11], v[112:113], v[84:85], v[82:83] op_sel_hi:[1,0,1] neg_lo:[0,1,0] neg_hi:[0,1,0]
	ds_read_b128 v[20:23], v94 offset:18432
	ds_read_b128 v[28:31], v94 offset:2048
	s_waitcnt lgkmcnt(5)
	v_pk_mul_f32 v[16:17], v[8:9], v[16:17]
	v_pk_mul_f32 v[118:119], v[8:9], v[118:119]
	v_pk_fma_f32 v[16:17], v[10:11], v[18:19], v[16:17]
	v_pk_fma_f32 v[118:119], v[10:11], v[120:121], v[118:119]
	v_add_f32_e32 v16, v16, v17
	s_waitcnt lgkmcnt(3)
	v_pk_mul_f32 v[12:13], v[12:13], v[74:75] op_sel_hi:[1,0]
	v_pk_mul_f32 v[14:15], v[14:15], v[74:75] op_sel_hi:[1,0]
	v_add_f32_dpp v16, v16, v16 quad_perm:[1,0,3,2] row_mask:0xf bank_mask:0xf bound_ctrl:1
	s_waitcnt lgkmcnt(2)
	v_pk_fma_f32 v[12:13], v[8:9], v[24:25], v[12:13]
	v_pk_fma_f32 v[14:15], v[10:11], v[26:27], v[14:15]
	v_add_f32_dpp v16, v16, v16 quad_perm:[2,3,0,1] row_mask:0xf bank_mask:0xf bound_ctrl:1
	v_add_f32_e32 v118, v118, v119
	ds_write_b32 v106, v118 offset:7168
	v_add_f32_dpp v16, v16, v16 row_half_mirror row_mask:0xf bank_mask:0xf bound_ctrl:1
	ds_read_b128 v[84:87], v94 offset:14592
	ds_read_b128 v[80:83], v94 offset:10496
	v_add_f32_dpp v16, v16, v16 row_mirror row_mask:0xf bank_mask:0xf bound_ctrl:1
	ds_read_b32 v88, v39 offset:22784
	ds_read_b128 v[114:117], v94 offset:6400
	s_waitcnt lgkmcnt(6)
	v_pk_fma_f32 v[8:9], v[20:21], v[16:17], v[12:13] op_sel_hi:[1,0,1] neg_lo:[0,1,0] neg_hi:[0,1,0]
	v_pk_fma_f32 v[10:11], v[22:23], v[16:17], v[14:15] op_sel_hi:[1,0,1] neg_lo:[0,1,0] neg_hi:[0,1,0]
	ds_read_b128 v[110:113], v94 offset:18688
	ds_read_b128 v[118:121], v94 offset:2304
	s_waitcnt lgkmcnt(5)
	v_pk_mul_f32 v[84:85], v[8:9], v[84:85]
	v_pk_mul_f32 v[28:29], v[8:9], v[28:29]
	v_pk_fma_f32 v[84:85], v[10:11], v[86:87], v[84:85]
	v_pk_fma_f32 v[28:29], v[10:11], v[30:31], v[28:29]
	v_add_f32_e32 v84, v84, v85
	s_waitcnt lgkmcnt(3)
	v_pk_mul_f32 v[80:81], v[80:81], v[88:89] op_sel_hi:[1,0]
	v_pk_mul_f32 v[82:83], v[82:83], v[88:89] op_sel_hi:[1,0]
	v_add_f32_dpp v84, v84, v84 quad_perm:[1,0,3,2] row_mask:0xf bank_mask:0xf bound_ctrl:1
	s_waitcnt lgkmcnt(2)
	v_pk_fma_f32 v[80:81], v[8:9], v[114:115], v[80:81]
	v_pk_fma_f32 v[82:83], v[10:11], v[116:117], v[82:83]
	v_add_f32_dpp v84, v84, v84 quad_perm:[2,3,0,1] row_mask:0xf bank_mask:0xf bound_ctrl:1
	v_add_f32_e32 v28, v28, v29
	ds_write_b32 v106, v28 offset:8192
	v_add_f32_dpp v84, v84, v84 row_half_mirror row_mask:0xf bank_mask:0xf bound_ctrl:1
	ds_read_b128 v[16:19], v94 offset:14848
	ds_read_b128 v[12:15], v94 offset:10752
	v_add_f32_dpp v84, v84, v84 row_mirror row_mask:0xf bank_mask:0xf bound_ctrl:1
	ds_read_b32 v74, v39 offset:23040
	ds_read_b128 v[24:27], v94 offset:6656
	s_waitcnt lgkmcnt(6)
	v_pk_fma_f32 v[8:9], v[110:111], v[84:85], v[80:81] op_sel_hi:[1,0,1] neg_lo:[0,1,0] neg_hi:[0,1,0]
	v_pk_fma_f32 v[10:11], v[112:113], v[84:85], v[82:83] op_sel_hi:[1,0,1] neg_lo:[0,1,0] neg_hi:[0,1,0]
	ds_read_b128 v[20:23], v94 offset:18944
	ds_read_b128 v[28:31], v94 offset:2560
	s_waitcnt lgkmcnt(5)
	v_pk_mul_f32 v[16:17], v[8:9], v[16:17]
	v_pk_mul_f32 v[118:119], v[8:9], v[118:119]
	v_pk_fma_f32 v[16:17], v[10:11], v[18:19], v[16:17]
	v_pk_fma_f32 v[118:119], v[10:11], v[120:121], v[118:119]
	v_add_f32_e32 v16, v16, v17
	s_waitcnt lgkmcnt(3)
	v_pk_mul_f32 v[12:13], v[12:13], v[74:75] op_sel_hi:[1,0]
	v_pk_mul_f32 v[14:15], v[14:15], v[74:75] op_sel_hi:[1,0]
	v_add_f32_dpp v16, v16, v16 quad_perm:[1,0,3,2] row_mask:0xf bank_mask:0xf bound_ctrl:1
	s_waitcnt lgkmcnt(2)
	v_pk_fma_f32 v[12:13], v[8:9], v[24:25], v[12:13]
	v_pk_fma_f32 v[14:15], v[10:11], v[26:27], v[14:15]
	v_add_f32_dpp v16, v16, v16 quad_perm:[2,3,0,1] row_mask:0xf bank_mask:0xf bound_ctrl:1
	v_add_f32_e32 v118, v118, v119
	ds_write_b32 v106, v118 offset:9216
	v_add_f32_dpp v16, v16, v16 row_half_mirror row_mask:0xf bank_mask:0xf bound_ctrl:1
	ds_read_b128 v[84:87], v94 offset:15104
	ds_read_b128 v[80:83], v94 offset:11008
	v_add_f32_dpp v16, v16, v16 row_mirror row_mask:0xf bank_mask:0xf bound_ctrl:1
	ds_read_b32 v88, v39 offset:23296
	ds_read_b128 v[114:117], v94 offset:6912
	s_waitcnt lgkmcnt(6)
	v_pk_fma_f32 v[8:9], v[20:21], v[16:17], v[12:13] op_sel_hi:[1,0,1] neg_lo:[0,1,0] neg_hi:[0,1,0]
	v_pk_fma_f32 v[10:11], v[22:23], v[16:17], v[14:15] op_sel_hi:[1,0,1] neg_lo:[0,1,0] neg_hi:[0,1,0]
	ds_read_b128 v[110:113], v94 offset:19200
	ds_read_b128 v[118:121], v94 offset:2816
	s_waitcnt lgkmcnt(5)
	v_pk_mul_f32 v[84:85], v[8:9], v[84:85]
	v_pk_mul_f32 v[28:29], v[8:9], v[28:29]
	v_pk_fma_f32 v[84:85], v[10:11], v[86:87], v[84:85]
	v_pk_fma_f32 v[28:29], v[10:11], v[30:31], v[28:29]
	v_add_f32_e32 v84, v84, v85
	s_waitcnt lgkmcnt(3)
	v_pk_mul_f32 v[80:81], v[80:81], v[88:89] op_sel_hi:[1,0]
	v_pk_mul_f32 v[82:83], v[82:83], v[88:89] op_sel_hi:[1,0]
	v_add_f32_dpp v84, v84, v84 quad_perm:[1,0,3,2] row_mask:0xf bank_mask:0xf bound_ctrl:1
	s_waitcnt lgkmcnt(2)
	v_pk_fma_f32 v[80:81], v[8:9], v[114:115], v[80:81]
	v_pk_fma_f32 v[82:83], v[10:11], v[116:117], v[82:83]
	v_add_f32_dpp v84, v84, v84 quad_perm:[2,3,0,1] row_mask:0xf bank_mask:0xf bound_ctrl:1
	v_add_f32_e32 v28, v28, v29
	ds_write_b32 v106, v28 offset:10240
	v_add_f32_dpp v84, v84, v84 row_half_mirror row_mask:0xf bank_mask:0xf bound_ctrl:1
	ds_read_b128 v[16:19], v94 offset:15360
	ds_read_b128 v[12:15], v94 offset:11264
	v_add_f32_dpp v84, v84, v84 row_mirror row_mask:0xf bank_mask:0xf bound_ctrl:1
	ds_read_b32 v74, v39 offset:23552
	ds_read_b128 v[24:27], v94 offset:7168
	s_waitcnt lgkmcnt(6)
	v_pk_fma_f32 v[8:9], v[110:111], v[84:85], v[80:81] op_sel_hi:[1,0,1] neg_lo:[0,1,0] neg_hi:[0,1,0]
	v_pk_fma_f32 v[10:11], v[112:113], v[84:85], v[82:83] op_sel_hi:[1,0,1] neg_lo:[0,1,0] neg_hi:[0,1,0]
	ds_read_b128 v[20:23], v94 offset:19456
	ds_read_b128 v[28:31], v94 offset:3072
	s_waitcnt lgkmcnt(5)
	v_pk_mul_f32 v[16:17], v[8:9], v[16:17]
	v_pk_mul_f32 v[118:119], v[8:9], v[118:119]
	v_pk_fma_f32 v[16:17], v[10:11], v[18:19], v[16:17]
	v_pk_fma_f32 v[118:119], v[10:11], v[120:121], v[118:119]
	v_add_f32_e32 v16, v16, v17
	s_waitcnt lgkmcnt(3)
	v_pk_mul_f32 v[12:13], v[12:13], v[74:75] op_sel_hi:[1,0]
	v_pk_mul_f32 v[14:15], v[14:15], v[74:75] op_sel_hi:[1,0]
	v_add_f32_dpp v16, v16, v16 quad_perm:[1,0,3,2] row_mask:0xf bank_mask:0xf bound_ctrl:1
	s_waitcnt lgkmcnt(2)
	v_pk_fma_f32 v[12:13], v[8:9], v[24:25], v[12:13]
	v_pk_fma_f32 v[14:15], v[10:11], v[26:27], v[14:15]
	v_add_f32_dpp v16, v16, v16 quad_perm:[2,3,0,1] row_mask:0xf bank_mask:0xf bound_ctrl:1
	v_add_f32_e32 v118, v118, v119
	ds_write_b32 v106, v118 offset:11264
	v_add_f32_dpp v16, v16, v16 row_half_mirror row_mask:0xf bank_mask:0xf bound_ctrl:1
	ds_read_b128 v[84:87], v94 offset:15616
	ds_read_b128 v[80:83], v94 offset:11520
	v_add_f32_dpp v16, v16, v16 row_mirror row_mask:0xf bank_mask:0xf bound_ctrl:1
	ds_read_b32 v88, v39 offset:23808
	ds_read_b128 v[114:117], v94 offset:7424
	s_waitcnt lgkmcnt(6)
	v_pk_fma_f32 v[8:9], v[20:21], v[16:17], v[12:13] op_sel_hi:[1,0,1] neg_lo:[0,1,0] neg_hi:[0,1,0]
	v_pk_fma_f32 v[10:11], v[22:23], v[16:17], v[14:15] op_sel_hi:[1,0,1] neg_lo:[0,1,0] neg_hi:[0,1,0]
	ds_read_b128 v[110:113], v94 offset:19712
	ds_read_b128 v[118:121], v94 offset:3328
	s_waitcnt lgkmcnt(5)
	v_pk_mul_f32 v[84:85], v[8:9], v[84:85]
	v_pk_mul_f32 v[28:29], v[8:9], v[28:29]
	v_pk_fma_f32 v[84:85], v[10:11], v[86:87], v[84:85]
	v_pk_fma_f32 v[28:29], v[10:11], v[30:31], v[28:29]
	v_add_f32_e32 v84, v84, v85
	s_waitcnt lgkmcnt(3)
	v_pk_mul_f32 v[80:81], v[80:81], v[88:89] op_sel_hi:[1,0]
	v_pk_mul_f32 v[82:83], v[82:83], v[88:89] op_sel_hi:[1,0]
	v_add_f32_dpp v84, v84, v84 quad_perm:[1,0,3,2] row_mask:0xf bank_mask:0xf bound_ctrl:1
	s_waitcnt lgkmcnt(2)
	v_pk_fma_f32 v[80:81], v[8:9], v[114:115], v[80:81]
	v_pk_fma_f32 v[82:83], v[10:11], v[116:117], v[82:83]
	v_add_f32_dpp v84, v84, v84 quad_perm:[2,3,0,1] row_mask:0xf bank_mask:0xf bound_ctrl:1
	v_add_f32_e32 v28, v28, v29
	ds_write_b32 v106, v28 offset:12288
	v_add_f32_dpp v84, v84, v84 row_half_mirror row_mask:0xf bank_mask:0xf bound_ctrl:1
	ds_read_b128 v[16:19], v94 offset:15872
	ds_read_b128 v[12:15], v94 offset:11776
	v_add_f32_dpp v84, v84, v84 row_mirror row_mask:0xf bank_mask:0xf bound_ctrl:1
	ds_read_b32 v74, v39 offset:24064
	ds_read_b128 v[24:27], v94 offset:7680
	s_waitcnt lgkmcnt(6)
	v_pk_fma_f32 v[8:9], v[110:111], v[84:85], v[80:81] op_sel_hi:[1,0,1] neg_lo:[0,1,0] neg_hi:[0,1,0]
	v_pk_fma_f32 v[10:11], v[112:113], v[84:85], v[82:83] op_sel_hi:[1,0,1] neg_lo:[0,1,0] neg_hi:[0,1,0]
	ds_read_b128 v[20:23], v94 offset:19968
	ds_read_b128 v[28:31], v94 offset:3584
	s_waitcnt lgkmcnt(5)
	v_pk_mul_f32 v[16:17], v[8:9], v[16:17]
	v_pk_mul_f32 v[118:119], v[8:9], v[118:119]
	v_pk_fma_f32 v[16:17], v[10:11], v[18:19], v[16:17]
	v_pk_fma_f32 v[118:119], v[10:11], v[120:121], v[118:119]
	v_add_f32_e32 v16, v16, v17
	s_waitcnt lgkmcnt(3)
	v_pk_mul_f32 v[12:13], v[12:13], v[74:75] op_sel_hi:[1,0]
	v_pk_mul_f32 v[14:15], v[14:15], v[74:75] op_sel_hi:[1,0]
	v_add_f32_dpp v16, v16, v16 quad_perm:[1,0,3,2] row_mask:0xf bank_mask:0xf bound_ctrl:1
	s_waitcnt lgkmcnt(2)
	v_pk_fma_f32 v[12:13], v[8:9], v[24:25], v[12:13]
	v_pk_fma_f32 v[14:15], v[10:11], v[26:27], v[14:15]
	v_add_f32_dpp v16, v16, v16 quad_perm:[2,3,0,1] row_mask:0xf bank_mask:0xf bound_ctrl:1
	v_add_f32_e32 v118, v118, v119
	ds_write_b32 v106, v118 offset:13312
	v_add_f32_dpp v16, v16, v16 row_half_mirror row_mask:0xf bank_mask:0xf bound_ctrl:1
	ds_read_b128 v[84:87], v94 offset:16128
	ds_read_b128 v[80:83], v94 offset:12032
	v_add_f32_dpp v16, v16, v16 row_mirror row_mask:0xf bank_mask:0xf bound_ctrl:1
	ds_read_b32 v88, v39 offset:24320
	ds_read_b128 v[114:117], v94 offset:7936
	s_waitcnt lgkmcnt(6)
	v_pk_fma_f32 v[8:9], v[20:21], v[16:17], v[12:13] op_sel_hi:[1,0,1] neg_lo:[0,1,0] neg_hi:[0,1,0]
	v_pk_fma_f32 v[10:11], v[22:23], v[16:17], v[14:15] op_sel_hi:[1,0,1] neg_lo:[0,1,0] neg_hi:[0,1,0]
	ds_read_b128 v[110:113], v94 offset:20224
	ds_read_b128 v[118:121], v94 offset:3840
	s_waitcnt lgkmcnt(5)
	v_pk_mul_f32 v[84:85], v[8:9], v[84:85]
	v_pk_mul_f32 v[28:29], v[8:9], v[28:29]
	v_pk_fma_f32 v[84:85], v[10:11], v[86:87], v[84:85]
	v_pk_fma_f32 v[28:29], v[10:11], v[30:31], v[28:29]
	v_add_f32_e32 v84, v84, v85
	s_waitcnt lgkmcnt(3)
	v_pk_mul_f32 v[80:81], v[80:81], v[88:89] op_sel_hi:[1,0]
	v_pk_mul_f32 v[82:83], v[82:83], v[88:89] op_sel_hi:[1,0]
	v_add_f32_dpp v84, v84, v84 quad_perm:[1,0,3,2] row_mask:0xf bank_mask:0xf bound_ctrl:1
	s_waitcnt lgkmcnt(2)
	v_pk_fma_f32 v[80:81], v[8:9], v[114:115], v[80:81]
	v_pk_fma_f32 v[82:83], v[10:11], v[116:117], v[82:83]
	v_add_f32_dpp v84, v84, v84 quad_perm:[2,3,0,1] row_mask:0xf bank_mask:0xf bound_ctrl:1
	v_add_f32_e32 v28, v28, v29
	ds_write_b32 v106, v28 offset:14336
	v_add_f32_dpp v84, v84, v84 row_half_mirror row_mask:0xf bank_mask:0xf bound_ctrl:1
	s_nop 1
	v_add_f32_dpp v84, v84, v84 row_mirror row_mask:0xf bank_mask:0xf bound_ctrl:1
	s_waitcnt lgkmcnt(2)
	v_pk_fma_f32 v[8:9], v[110:111], v[84:85], v[80:81] op_sel_hi:[1,0,1] neg_lo:[0,1,0] neg_hi:[0,1,0]
	v_pk_fma_f32 v[10:11], v[112:113], v[84:85], v[82:83] op_sel_hi:[1,0,1] neg_lo:[0,1,0] neg_hi:[0,1,0]
	s_waitcnt lgkmcnt(1)
	v_pk_mul_f32 v[118:119], v[8:9], v[118:119]
	s_nop 0
	v_pk_fma_f32 v[118:119], v[10:11], v[120:121], v[118:119]
	s_nop 0
	v_add_f32_e32 v118, v118, v119
	ds_write_b32 v106, v118 offset:15360
	s_waitcnt lgkmcnt(0)
	s_barrier
	ds_read_b128 v[12:15], v107 offset:24576
	ds_read_b128 v[16:19], v107 offset:24592
	ds_read_b128 v[20:23], v107 offset:24608
	ds_read_b128 v[24:27], v107 offset:24624
	s_waitcnt lgkmcnt(3)
	v_mov_b32_e32 v28, v13
	v_mov_b32_e32 v29, v14
	s_waitcnt lgkmcnt(2)
	v_mov_b32_e32 v30, v17
	v_mov_b32_e32 v31, v18
	v_mov_b32_e32 v13, v15
	v_mov_b32_e32 v17, v19
	v_pk_add_f32 v[12:13], v[28:29], v[12:13]
	v_pk_add_f32 v[14:15], v[30:31], v[16:17]
	s_waitcnt lgkmcnt(1)
	v_mov_b32_e32 v16, v21
	v_mov_b32_e32 v18, v23
	v_pk_add_f32 v[12:13], v[12:13], v[12:13] op_sel:[0,1] op_sel_hi:[1,0]
	v_pk_add_f32 v[14:15], v[14:15], v[14:15] op_sel:[0,1] op_sel_hi:[1,0]
	v_pk_add_f32 v[16:17], v[20:21], v[16:17]
	v_pk_add_f32 v[18:19], v[22:23], v[18:19]
	s_waitcnt lgkmcnt(0)
	v_mov_b32_e32 v13, v24
	v_mov_b32_e32 v15, v25
	v_mov_b32_e32 v17, v26
	v_mov_b32_e32 v19, v27
	v_pk_add_f32 v[12:13], v[12:13], v[14:15]
	v_pk_add_f32 v[14:15], v[16:17], v[18:19]
	s_nop 0
	v_pk_add_f32 v[12:13], v[12:13], v[14:15]
	s_nop 0
	v_pk_add_f32 v[12:13], v[12:13], v[12:13] op_sel:[0,1] op_sel_hi:[1,0]
	s_nop 0
	v_bfe_u32 v13, v12, 16, 1
	v_add3_u32 v14, v12, v13, s33
	v_lshl_add_u32 v12, s89, 4, v38
	v_ashrrev_i32_e32 v13, 31, v12
	v_lshlrev_b64 v[12:13], 11, v[12:13]
	v_lshl_add_u64 v[12:13], v[50:51], 0, v[12:13]
	global_store_short_d16_hi v[12:13], v14, off
	s_branch .LBB0_200
